# conv_gu walks its items in descending k order: the rows the column-maximum pass read last are converted first (memory-side cache reuse)
# baseline (speedup 1.0000x reference)
.LBB0_63:
	s_or_b64 exec, exec, s[82:83]
	s_xor_b64 s[82:83], s[80:81], -1
	s_andn2_b64 vcc, exec, s[76:77]
	s_waitcnt lgkmcnt(0)
	s_barrier
	s_cbranch_vccnz .LBB0_7
	v_readlane_b32 s8, v254, 0
	s_and_b64 s[40:41], s[80:81], exec
	v_readlane_b32 s9, v254, 1
	v_readlane_b32 s10, v254, 2
	v_readlane_b32 s11, v254, 3
	s_cselect_b32 s41, s9, s11
	s_cselect_b32 s42, s8, s10
	v_readlane_b32 s8, v254, 52
	v_readlane_b32 s9, v254, 53
	s_cselect_b32 s40, 0, 0x80
	s_lshl_b32 s43, s8, 5
	s_lshl_b32 s44, s8, 6
	s_mov_b32 s45, s8
	s_sub_i32 s45, 0x55ff, s45
	s_lshl_b32 s43, s45, 5
	s_lshl_b32 s44, s45, 6
	v_readlane_b32 s8, v254, 61
	v_readlane_b32 s12, v254, 4
	v_readlane_b32 s13, v254, 5
	v_readlane_b32 s14, v254, 6
	v_readlane_b32 s15, v254, 7
	v_readlane_b32 s9, v254, 62
.LBB0_65:
	s_mul_hi_i32 s46, s45, 0x2fa0be83
	s_lshr_b32 s47, s46, 31
	s_ashr_i32 s46, s46, 6
	s_add_i32 s84, s46, s47
	s_mul_i32 s46, s84, 0xffffd500
	s_mul_i32 s47, s84, 0xffffaa00
	s_add_i32 s46, s43, s46
	s_add_i32 s47, s44, s47
	s_and_b32 s48, s46, 0x60
	s_and_b32 s47, s47, 0xffffff00
	s_or_b32 s48, s48, s40
	s_mul_i32 s80, s84, 0x2b0000
	s_or_b32 s48, s48, s47
	s_mul_hi_i32 s49, s84, 0x2b0000
	s_add_u32 s80, s42, s80
	s_addc_u32 s49, s41, s49
	s_ashr_i32 s47, s46, 31
	s_lshl_b64 s[46:47], s[46:47], 2
	s_add_u32 s46, s80, s46
	s_addc_u32 s47, s49, s47
	v_mov_b32_e32 v13, v143
	v_mov_b32_e32 v15, v143
	v_mov_b32_e32 v17, v143
	v_mov_b32_e32 v19, v143
	v_mov_b32_e32 v21, v143
	v_lshl_add_u64 v[2:3], s[46:47], 0, v[142:143]
	v_lshl_add_u64 v[48:49], v[2:3], 0, v[12:13]
	v_lshl_add_u64 v[26:27], v[2:3], 0, v[14:15]
	v_lshl_add_u64 v[36:37], v[2:3], 0, v[16:17]
	v_lshl_add_u64 v[40:41], v[2:3], 0, v[18:19]
	v_lshl_add_u64 v[2:3], v[2:3], 0, v[20:21]
	global_load_dwordx4 v[22:25], v[48:49], off nt
	s_nop 0
	global_load_dwordx4 v[26:29], v[26:27], off nt
	s_nop 0
	global_load_dwordx4 v[36:39], v[36:37], off nt
	s_nop 0
	global_load_dwordx4 v[40:43], v[40:41], off nt
	s_nop 0
	global_load_dwordx4 v[44:47], v[2:3], off nt
	v_add_co_u32_e32 v2, vcc, s53, v48
	v_add_u32_e32 v35, v30, v31
	s_nop 0
	v_addc_co_u32_e32 v3, vcc, 0, v49, vcc
	v_add_co_u32_e32 v52, vcc, s79, v48
	v_add_u32_e32 v62, 0x420, v35
	s_nop 0
	v_addc_co_u32_e32 v53, vcc, 0, v49, vcc
	v_add_co_u32_e32 v56, vcc, s33, v48
	v_add_u32_e32 v63, 0x428, v35
	s_nop 0
	v_addc_co_u32_e32 v57, vcc, 0, v49, vcc
	global_load_dwordx4 v[48:51], v[2:3], off nt
	s_nop 0
	global_load_dwordx4 v[52:55], v[52:53], off nt
	s_nop 0
	global_load_dwordx4 v[56:59], v[56:57], off nt
	v_add_u32_e32 v65, 0x840, v35
	v_add_u32_e32 v66, 0x848, v35
	v_add_u32_e32 v67, 0xc60, v35
	v_add_u32_e32 v68, 0xc68, v35
	v_add_u32_e32 v69, 0x1080, v35
	v_add_u32_e32 v70, 0x1088, v35
	v_add_u32_e32 v71, 0x14a0, v35
	v_add_u32_e32 v72, 0x14a8, v35
	v_add_u32_e32 v73, 0x18c0, v35
	v_add_u32_e32 v74, 0x18c8, v35
	v_add_u32_e32 v75, 0x1ce0, v35
	v_add_u32_e32 v76, 0x1ce8, v35
	s_ashr_i32 s49, s48, 31
	v_lshl_add_u64 v[4:5], s[48:49], 2, v[10:11]
	s_lshl_b64 s[80:81], s[48:49], 12
	s_add_u32 s46, s51, s80
	s_addc_u32 s47, s52, s81
	s_lshl_b32 s48, s84, 6
	s_ashr_i32 s49, s48, 31
	s_add_u32 s46, s46, s48
	s_addc_u32 s47, s47, s49
	v_lshl_add_u64 v[2:3], s[46:47], 0, v[144:145]
	v_add_u32_e32 v64, 0x400, v149
	v_lshl_add_u64 v[60:61], v[2:3], 0, v[6:7]
	s_sub_i32 s45, s45, s8
	s_sub_i32 s43, s43, s37
	s_sub_i32 s44, s44, s55
	s_cmp_gt_i32 s45, -1
	s_waitcnt vmcnt(7)
	ds_write2_b32 v35, v22, v23 offset1:1
	ds_write2_b32 v35, v24, v25 offset0:2 offset1:3
	s_waitcnt vmcnt(6)
	ds_write2_b32 v69, v26, v27 offset1:1
	ds_write2_b32 v70, v28, v29 offset1:1
	s_waitcnt vmcnt(5)
	ds_write2_b32 v71, v36, v37 offset1:1
	ds_write2_b32 v72, v38, v39 offset1:1
	s_waitcnt vmcnt(4)
	ds_write2_b32 v73, v40, v41 offset1:1
	ds_write2_b32 v74, v42, v43 offset1:1
	s_waitcnt vmcnt(3)
	ds_write2_b32 v75, v44, v45 offset1:1
	ds_write2_b32 v76, v46, v47 offset1:1
	s_waitcnt vmcnt(2)
	ds_write2_b32 v62, v48, v49 offset1:1
	ds_write2_b32 v63, v50, v51 offset1:1
	s_waitcnt vmcnt(1)
	ds_write2_b32 v65, v52, v53 offset1:1
	ds_write2_b32 v66, v54, v55 offset1:1
	s_waitcnt vmcnt(0)
	ds_write2_b32 v67, v56, v57 offset1:1
	ds_write2_b32 v68, v58, v59 offset1:1
	s_waitcnt lgkmcnt(0)
	global_load_dword v13, v[4:5], off
	ds_read2_b32 v[26:27], v149 offset1:16
	ds_read2_b32 v[28:29], v149 offset0:33 offset1:49
	ds_read2_b32 v[36:37], v149 offset0:66 offset1:82
	ds_read2_b32 v[38:39], v149 offset0:99 offset1:115
	ds_read2_b32 v[40:41], v149 offset0:132 offset1:148
	ds_read2_b32 v[42:43], v149 offset0:165 offset1:181
	ds_read2_b32 v[44:45], v149 offset0:198 offset1:214
	ds_read2_b32 v[46:47], v149 offset0:231 offset1:247
	ds_read2_b32 v[48:49], v64 offset0:8 offset1:24
	ds_read2_b32 v[50:51], v64 offset0:41 offset1:57
	ds_read2_b32 v[52:53], v64 offset0:74 offset1:90
	ds_read2_b32 v[54:55], v64 offset0:107 offset1:123
	ds_read2_b32 v[56:57], v64 offset0:140 offset1:156
	ds_read2_b32 v[58:59], v64 offset0:173 offset1:189
	ds_read2_b32 v[62:63], v64 offset0:206 offset1:222
	ds_read2_b32 v[64:65], v64 offset0:239 offset1:255
	s_waitcnt lgkmcnt(14)
	v_mov_b32_e32 v22, v26
	v_mov_b32_e32 v24, v28
	s_waitcnt lgkmcnt(10)
	v_mov_b32_e32 v25, v42
	v_mov_b32_e32 v68, v38
	s_waitcnt lgkmcnt(8)
	v_mov_b32_e32 v69, v46
	s_waitcnt lgkmcnt(6)
	v_mov_b32_e32 v72, v50
	s_waitcnt lgkmcnt(2)
	v_mov_b32_e32 v73, v58
	v_mov_b32_e32 v74, v52
	s_waitcnt lgkmcnt(1)
	v_mov_b32_e32 v75, v62
	v_mov_b32_e32 v76, v54
	s_waitcnt lgkmcnt(0)
	v_mov_b32_e32 v77, v64
	v_mov_b32_e32 v23, v40
	v_mov_b32_e32 v66, v36
	v_mov_b32_e32 v67, v44
	v_mov_b32_e32 v70, v48
	v_mov_b32_e32 v71, v56
	v_mov_b32_e32 v40, v27
	v_mov_b32_e32 v42, v29
	v_mov_b32_e32 v44, v37
	v_mov_b32_e32 v46, v39
	v_mov_b32_e32 v56, v49
	v_mov_b32_e32 v58, v51
	v_mov_b32_e32 v62, v53
	v_mov_b32_e32 v64, v55
	s_waitcnt vmcnt(0)
	v_div_scale_f32 v15, s[46:47], v13, v13, s90
	v_rcp_f32_e32 v19, v15
	v_div_scale_f32 v17, vcc, s90, v13, s90
	v_fma_f32 v21, -v15, v19, 1.0
	v_fmac_f32_e32 v19, v21, v19
	v_mul_f32_e32 v21, v17, v19
	v_fma_f32 v26, -v15, v21, v17
	v_fmac_f32_e32 v21, v26, v19
	v_fma_f32 v15, -v15, v21, v17
	v_div_fmas_f32 v15, v15, v19, v21
	v_div_fixup_f32 v15, v15, v13, s90
	v_cmp_lt_f32_e32 vcc, 0, v13
	s_nop 1
	v_cndmask_b32_e32 v26, 0, v15, vcc
	v_pk_fma_f32 v[24:25], v[24:25], v[26:27], s[78:79] op_sel_hi:[1,0,0]
	v_pk_fma_f32 v[68:69], v[68:69], v[26:27], s[78:79] op_sel_hi:[1,0,0]
	v_pk_fma_f32 v[72:73], v[72:73], v[26:27], s[78:79] op_sel_hi:[1,0,0]
	v_pk_fma_f32 v[74:75], v[74:75], v[26:27], s[78:79] op_sel_hi:[1,0,0]
	v_pk_fma_f32 v[76:77], v[76:77], v[26:27], s[78:79] op_sel_hi:[1,0,0]
	v_pk_fma_f32 v[22:23], v[22:23], v[26:27], s[78:79] op_sel_hi:[1,0,0]
	v_pk_fma_f32 v[66:67], v[66:67], v[26:27], s[78:79] op_sel_hi:[1,0,0]
	v_pk_fma_f32 v[70:71], v[70:71], v[26:27], s[78:79] op_sel_hi:[1,0,0]
	v_lshlrev_b32_e32 v13, 8, v25
	v_lshlrev_b32_e32 v15, 8, v24
	v_lshlrev_b32_e32 v21, 24, v69
	v_lshlrev_b32_e32 v24, 24, v68
	v_lshlrev_b32_e32 v25, 8, v73
	v_lshlrev_b32_e32 v26, 8, v72
	v_lshlrev_b32_e32 v28, 16, v75
	v_lshlrev_b32_e32 v35, 16, v74
	v_lshlrev_b32_e32 v36, 24, v77
	v_lshlrev_b32_e32 v38, 24, v76
	v_lshlrev_b32_e32 v17, 16, v67
	v_lshlrev_b32_e32 v19, 16, v66
	v_and_b32_e32 v13, 0xff00, v13
	v_and_b32_e32 v15, 0xff00, v15
	v_or_b32_sdwa v21, v21, v23 dst_sel:DWORD dst_unused:UNUSED_PAD src0_sel:DWORD src1_sel:BYTE_0
	v_or_b32_sdwa v22, v24, v22 dst_sel:DWORD dst_unused:UNUSED_PAD src0_sel:DWORD src1_sel:BYTE_0
	v_and_b32_e32 v23, 0xff00, v25
	v_and_b32_e32 v24, 0xff00, v26
	v_and_b32_e32 v25, 0xff0000, v28
	v_and_b32_e32 v26, 0xff0000, v35
	v_or_b32_sdwa v28, v36, v71 dst_sel:DWORD dst_unused:UNUSED_PAD src0_sel:DWORD src1_sel:BYTE_0
	v_or_b32_sdwa v35, v38, v70 dst_sel:DWORD dst_unused:UNUSED_PAD src0_sel:DWORD src1_sel:BYTE_0
	v_and_b32_e32 v17, 0xff0000, v17
	v_and_b32_e32 v19, 0xff0000, v19
	v_or_b32_e32 v13, v21, v13
	v_or_b32_e32 v15, v22, v15
	v_or_b32_e32 v21, v28, v23
	v_or_b32_e32 v24, v35, v24
	v_or_b32_e32 v23, v13, v17
	v_or_b32_e32 v22, v15, v19
	v_or_b32_e32 v25, v21, v25
	v_or_b32_e32 v24, v24, v26
	global_store_dwordx4 v[60:61], v[22:25], off
	global_load_dword v4, v[4:5], off offset:64
	s_nop 0
	v_lshl_add_u64 v[22:23], v[2:3], 0, v[146:147]
	s_waitcnt vmcnt(0)
	v_div_scale_f32 v2, s[46:47], v4, v4, s90
	v_rcp_f32_e32 v5, v2
	v_div_scale_f32 v3, vcc, s90, v4, s90
	v_fma_f32 v13, -v2, v5, 1.0
	v_fmac_f32_e32 v5, v13, v5
	v_mul_f32_e32 v13, v3, v5
	v_fma_f32 v15, -v2, v13, v3
	v_fmac_f32_e32 v13, v15, v5
	v_fma_f32 v2, -v2, v13, v3
	v_div_fmas_f32 v2, v2, v5, v13
	v_div_fixup_f32 v2, v2, v4, s90
	v_cmp_lt_f32_e32 vcc, 0, v4
	s_nop 1
	v_cndmask_b32_e32 v2, 0, v2, vcc
	v_pk_fma_f32 v[4:5], v[40:41], v[2:3], s[78:79] op_sel_hi:[1,0,0]
	v_pk_fma_f32 v[24:25], v[42:43], v[2:3], s[78:79] op_sel_hi:[1,0,0]
	v_pk_fma_f32 v[26:27], v[44:45], v[2:3], s[78:79] op_sel_hi:[1,0,0]
	v_pk_fma_f32 v[28:29], v[46:47], v[2:3], s[78:79] op_sel_hi:[1,0,0]
	v_pk_fma_f32 v[36:37], v[56:57], v[2:3], s[78:79] op_sel_hi:[1,0,0]
	v_pk_fma_f32 v[38:39], v[58:59], v[2:3], s[78:79] op_sel_hi:[1,0,0]
	v_pk_fma_f32 v[40:41], v[62:63], v[2:3], s[78:79] op_sel_hi:[1,0,0]
	v_pk_fma_f32 v[2:3], v[64:65], v[2:3], s[78:79] op_sel_hi:[1,0,0]
	v_lshlrev_b32_e32 v13, 8, v25
	v_lshlrev_b32_e32 v15, 8, v24
	v_lshlrev_b32_e32 v19, 16, v26
	v_lshlrev_b32_e32 v21, 24, v29
	v_lshlrev_b32_e32 v24, 24, v28
	v_lshlrev_b32_e32 v25, 8, v39
	v_lshlrev_b32_e32 v26, 8, v38
	v_lshlrev_b32_e32 v3, 24, v3
	v_lshlrev_b32_e32 v2, 24, v2
	v_lshlrev_b32_e32 v17, 16, v27
	v_lshlrev_b32_e32 v27, 16, v41
	v_lshlrev_b32_e32 v28, 16, v40
	v_and_b32_e32 v13, 0xff00, v13
	v_and_b32_e32 v15, 0xff00, v15
	v_or_b32_sdwa v5, v21, v5 dst_sel:DWORD dst_unused:UNUSED_PAD src0_sel:DWORD src1_sel:BYTE_0
	v_or_b32_sdwa v4, v24, v4 dst_sel:DWORD dst_unused:UNUSED_PAD src0_sel:DWORD src1_sel:BYTE_0
	v_and_b32_e32 v21, 0xff00, v25
	v_and_b32_e32 v24, 0xff00, v26
	v_or_b32_sdwa v3, v3, v37 dst_sel:DWORD dst_unused:UNUSED_PAD src0_sel:DWORD src1_sel:BYTE_0
	v_or_b32_sdwa v2, v2, v36 dst_sel:DWORD dst_unused:UNUSED_PAD src0_sel:DWORD src1_sel:BYTE_0
	v_and_b32_e32 v17, 0xff0000, v17
	v_and_b32_e32 v19, 0xff0000, v19
	v_and_b32_e32 v25, 0xff0000, v27
	v_and_b32_e32 v26, 0xff0000, v28
	v_or_b32_e32 v5, v5, v13
	v_or_b32_e32 v4, v4, v15
	v_or_b32_e32 v13, v3, v21
	v_or_b32_e32 v15, v2, v24
	v_or_b32_e32 v3, v5, v17
	v_or_b32_e32 v2, v4, v19
	v_or_b32_e32 v5, v13, v25
	v_or_b32_e32 v4, v15, v26
	global_store_dwordx4 v[22:23], v[2:5], off
	s_waitcnt lgkmcnt(0)
	s_cbranch_scc1 .LBB0_65
	s_branch .LBB0_7
